# GEMM K-loops (both): per-segment s_setprio flips inverted so the loading wave (LDS-DMA + ds_read issue, the critical path) outranks the MFMA wave; on top of stage B
# baseline (speedup 1.0000x reference)
; #define PG8_STAGE(bufoff, gbase, voff) do { _Pragma("unroll") for (int _i = 0; _i < 2; ++_i) \
;         __builtin_amdgcn_global_load_lds((const unsigned*)((const char*)(gbase) + (voff)[_i]), (LAS unsigned*)(lds + (bufoff) + ldsw + _i * 8192), 16, 0, 0); } while (0)
; #define PG8_LDA(dst, b, h) do { _Pragma("unroll") for (int m = 0; m < 4; ++m) _Pragma("unroll") for (int k = 0; k < 2; ++k) dst[m][k] = *(const LAS bf16x8*)(lds + PG8_SA(b, h) + aoff + m * 2048 + k * 1024); } while (0)
; #define PG8_LDB(dst, b, h) do { _Pragma("unroll") for (int n = 0; n < 2; ++n) _Pragma("unroll") for (int k = 0; k < 2; ++k) dst[n][k] = *(const LAS bf16x8*)(lds + PG8_SB(b, h) + boff + n * 2048 + k * 1024); } while (0)
; #define PG8_MMA(ai, bj, At, Bt) do { __builtin_amdgcn_s_setprio(1); _Pragma("unroll") for (int m = 0; m < 4; ++m) _Pragma("unroll") for (int n = 0; n < 2; ++n) _Pragma("unroll") for (int k = 0; k < 2; ++k) \
;         acc[ai][bj][m][n] = __builtin_amdgcn_mfma_f32_16x16x32_bf16(Bt[n][k], At[m][k], acc[ai][bj][m][n], 0, 0, 0); __builtin_amdgcn_s_setprio(0); } while (0)
; #define PG8_WAIT_V(n) asm volatile("s_waitcnt vmcnt(" #n ")" ::: "memory")
; #define PG8_WAIT_L(n) asm volatile("s_waitcnt lgkmcnt(" #n ")" ::: "memory")
; #define PG8_BAR __builtin_amdgcn_s_barrier()
; #define PG8_SCHED __builtin_amdgcn_sched_barrier(0)
; template <class Epi, class Sched, bool ALIGN_EPI = false, bool SP2 = true>
; DI void gemm_phase(LAS unsigned char* lds, const Gemm g, const Sched& S, const Epi& E, f32x4 (&acc)[2][2][4][2]) {
;     ...
;             PG8_LDB(B0, 0, 0); PG8_LDB(B1, 0, 1); PG8_SCHED; PG8_LDA(At, 0, 0); PG8_STAGE(PG8_SA(1, 1), a1 + hstep, voffA);
;             PG8_WAIT_V(8); PG8_WAIT_L(0); PG8_BAR; PG8_MMA(0, 0, At, B0); PG8_MMA(0, 1, At, B1); PG8_BAR; PG8_SCHED;
;             PG8_LDA(At, 0, 1); PG8_STAGE(PG8_SB(0, 0), b2, voffB); PG8_STAGE(PG8_SB(0, 1), b2 + hstep, voffB); PG8_STAGE(PG8_SA(0, 0), a2, voffA);
;             PG8_WAIT_V(8); PG8_WAIT_L(0); PG8_BAR; PG8_MMA(1, 0, At, B0); PG8_MMA(1, 1, At, B1); PG8_BAR; PG8_SCHED;
.LBB0_159:
	ds_read_b128 v[150:153], v164
	ds_read_b128 v[154:157], v164 offset:1024
	ds_read_b128 v[158:161], v164 offset:2048
	ds_read_b128 v[168:171], v164 offset:3072
	ds_read_b128 v[172:175], v165
	ds_read_b128 v[180:183], v165 offset:1024
	ds_read_b128 v[184:187], v165 offset:2048
	ds_read_b128 v[188:191], v165 offset:3072
	s_add_u32 s30, s0, 0xfffc0080
	s_addc_u32 s31, s1, -1
	s_cmp_eq_u32 s62, 12
	s_cselect_b32 s35, s25, s31
	s_cselect_b32 s34, s52, s30
	s_cselect_b32 s31, s23, s55
	s_cselect_b32 s30, s53, s54
	v_lshl_add_u64 v[176:177], s[0:1], 0, v[146:147]
	s_add_i32 m0, s74, 0xc000
	ds_read_b128 v[192:195], v166
	ds_read_b128 v[196:199], v166 offset:1024
	ds_read_b128 v[202:205], v166 offset:2048
	ds_read_b128 v[206:209], v166 offset:3072
	ds_read_b128 v[210:213], v166 offset:4096
	ds_read_b128 v[214:217], v166 offset:5120
	ds_read_b128 v[218:221], v166 offset:6144
	ds_read_b128 v[222:225], v166 offset:7168
	global_load_lds_dwordx4 v[176:177], off
	v_lshl_add_u64 v[176:177], s[0:1], 0, v[148:149]
	s_add_i32 m0, s74, 0xe000
	s_nop 0
	global_load_lds_dwordx4 v[176:177], off
	s_waitcnt vmcnt(8)
	s_waitcnt lgkmcnt(0)
	s_barrier
	s_setprio 0
	s_waitcnt lgkmcnt(0)
	v_mfma_f32_16x16x32_bf16 v[124:127], v[150:153], v[192:195], v[124:127]
	v_mfma_f32_16x16x32_bf16 v[120:123], v[158:161], v[192:195], v[120:123]
	v_mfma_f32_16x16x32_bf16 v[108:111], v[150:153], v[202:205], v[108:111]
	v_mfma_f32_16x16x32_bf16 v[104:107], v[158:161], v[202:205], v[104:107]
	v_mfma_f32_16x16x32_bf16 v[92:95], v[150:153], v[210:213], v[92:95]
	v_mfma_f32_16x16x32_bf16 v[88:91], v[158:161], v[210:213], v[88:91]
	v_mfma_f32_16x16x32_bf16 v[76:79], v[150:153], v[218:221], v[76:79]
	v_mfma_f32_16x16x32_bf16 v[72:75], v[158:161], v[218:221], v[72:75]
	v_mfma_f32_16x16x32_bf16 v[124:127], v[154:157], v[196:199], v[124:127]
	v_mfma_f32_16x16x32_bf16 v[120:123], v[168:171], v[196:199], v[120:123]
	v_mfma_f32_16x16x32_bf16 v[108:111], v[154:157], v[206:209], v[108:111]
	v_mfma_f32_16x16x32_bf16 v[104:107], v[168:171], v[206:209], v[104:107]
	v_mfma_f32_16x16x32_bf16 v[92:95], v[154:157], v[214:217], v[92:95]
	v_mfma_f32_16x16x32_bf16 v[88:91], v[168:171], v[214:217], v[88:91]
	v_mfma_f32_16x16x32_bf16 v[76:79], v[154:157], v[222:225], v[76:79]
	v_mfma_f32_16x16x32_bf16 v[72:75], v[168:171], v[222:225], v[72:75]
	s_setprio 1
	s_setprio 0
	v_mfma_f32_16x16x32_bf16 v[116:119], v[172:175], v[192:195], v[116:119]
	v_mfma_f32_16x16x32_bf16 v[112:115], v[184:187], v[192:195], v[112:115]
	v_mfma_f32_16x16x32_bf16 v[100:103], v[172:175], v[202:205], v[100:103]
	v_mfma_f32_16x16x32_bf16 v[96:99], v[184:187], v[202:205], v[96:99]
	v_mfma_f32_16x16x32_bf16 v[84:87], v[172:175], v[210:213], v[84:87]
	v_mfma_f32_16x16x32_bf16 v[80:83], v[184:187], v[210:213], v[80:83]
	v_mfma_f32_16x16x32_bf16 v[68:71], v[172:175], v[218:221], v[68:71]
	v_mfma_f32_16x16x32_bf16 v[64:67], v[184:187], v[218:221], v[64:67]
	v_mfma_f32_16x16x32_bf16 v[116:119], v[180:183], v[196:199], v[116:119]
	v_mfma_f32_16x16x32_bf16 v[112:115], v[188:191], v[196:199], v[112:115]
	v_mfma_f32_16x16x32_bf16 v[100:103], v[180:183], v[206:209], v[100:103]
	v_mfma_f32_16x16x32_bf16 v[96:99], v[188:191], v[206:209], v[96:99]
	v_mfma_f32_16x16x32_bf16 v[84:87], v[180:183], v[214:217], v[84:87]
	v_mfma_f32_16x16x32_bf16 v[80:83], v[188:191], v[214:217], v[80:83]
	v_mfma_f32_16x16x32_bf16 v[68:71], v[180:183], v[222:225], v[68:71]
	v_mfma_f32_16x16x32_bf16 v[64:67], v[188:191], v[222:225], v[64:67]
	s_setprio 1
	s_barrier
	s_add_i32 s63, s82, s39
	v_lshl_add_u64 v[176:177], s[30:31], 0, v[130:131]
	s_mov_b32 m0, s63
	ds_read_b128 v[192:195], v166 offset:16384
	ds_read_b128 v[196:199], v166 offset:17408
	ds_read_b128 v[202:205], v166 offset:18432
	ds_read_b128 v[206:209], v166 offset:19456
	ds_read_b128 v[210:213], v166 offset:20480
	ds_read_b128 v[214:217], v166 offset:21504
	ds_read_b128 v[218:221], v166 offset:22528
	ds_read_b128 v[222:225], v166 offset:23552
	global_load_lds_dwordx4 v[176:177], off
	s_add_i32 m0, s63, 0x2000
	s_add_u32 s72, s30, 0x10000
	v_lshl_add_u64 v[226:227], s[30:31], 0, v[134:135]
	s_addc_u32 s73, s31, 0
	s_add_i32 s63, s83, s39
	global_load_lds_dwordx4 v[226:227], off
	v_lshl_add_u64 v[228:229], s[72:73], 0, v[130:131]
	s_mov_b32 m0, s63
	v_lshl_add_u64 v[230:231], s[34:35], 0, v[132:133]
	global_load_lds_dwordx4 v[228:229], off
	v_lshl_add_u64 v[228:229], s[72:73], 0, v[134:135]
	s_add_i32 m0, s63, 0x2000
	s_nop 0
	global_load_lds_dwordx4 v[228:229], off
	v_lshl_add_u64 v[228:229], s[34:35], 0, v[128:129]
	s_mov_b32 m0, s74
	s_nop 0
	global_load_lds_dwordx4 v[228:229], off
	s_mov_b32 m0, s75
	s_nop 0
	global_load_lds_dwordx4 v[230:231], off
	s_waitcnt vmcnt(8)
	s_waitcnt lgkmcnt(0)
	s_barrier
; #define PG8_STAGE(bufoff, gbase, voff) do { _Pragma("unroll") for (int _i = 0; _i < 2; ++_i) \
;         __builtin_amdgcn_global_load_lds((const unsigned*)((const char*)(gbase) + (voff)[_i]), (LAS unsigned*)(lds + (bufoff) + ldsw + _i * 8192), 16, 0, 0); } while (0)
; #define PG8_LDA(dst, b, h) do { _Pragma("unroll") for (int m = 0; m < 4; ++m) _Pragma("unroll") for (int k = 0; k < 2; ++k) dst[m][k] = *(const LAS bf16x8*)(lds + PG8_SA(b, h) + aoff + m * 2048 + k * 1024); } while (0)
; #define PG8_LDB(dst, b, h) do { _Pragma("unroll") for (int n = 0; n < 2; ++n) _Pragma("unroll") for (int k = 0; k < 2; ++k) dst[n][k] = *(const LAS bf16x8*)(lds + PG8_SB(b, h) + boff + n * 2048 + k * 1024); } while (0)
; #define PG8_MMA(ai, bj, At, Bt) do { __builtin_amdgcn_s_setprio(1); _Pragma("unroll") for (int m = 0; m < 4; ++m) _Pragma("unroll") for (int n = 0; n < 2; ++n) _Pragma("unroll") for (int k = 0; k < 2; ++k) \
;         acc[ai][bj][m][n] = __builtin_amdgcn_mfma_f32_16x16x32_bf16(Bt[n][k], At[m][k], acc[ai][bj][m][n], 0, 0, 0); __builtin_amdgcn_s_setprio(0); } while (0)
; #define PG8_WAIT_V(n) asm volatile("s_waitcnt vmcnt(" #n ")" ::: "memory")
; #define PG8_WAIT_L(n) asm volatile("s_waitcnt lgkmcnt(" #n ")" ::: "memory")
; #define PG8_BAR __builtin_amdgcn_s_barrier()
; #define PG8_SCHED __builtin_amdgcn_sched_barrier(0)
; template <class Epi, class Sched, bool ALIGN_EPI = false, bool SP2 = true>
; DI void gemm_phase(LAS unsigned char* lds, const Gemm g, const Sched& S, const Epi& E, f32x4 (&acc)[2][2][4][2]) {
;     ...
;             PG8_WAIT_V(8); PG8_WAIT_L(0); PG8_BAR; PG8_MMA(1, 0, At, B0); PG8_MMA(1, 1, At, B1); PG8_BAR; PG8_SCHED;
;             PG8_LDB(B0, 1, 0); PG8_LDB(B1, 1, 1); PG8_SCHED; PG8_LDA(At, 1, 0); PG8_STAGE(PG8_SA(0, 1), a2 + hstep, voffA);
;             PG8_WAIT_V(8); PG8_WAIT_L(0); PG8_BAR; PG8_MMA(0, 0, At, B0); PG8_MMA(0, 1, At, B1); PG8_BAR; PG8_SCHED;
	s_setprio 0
	s_waitcnt lgkmcnt(0)
	v_mfma_f32_16x16x32_bf16 v[60:63], v[150:153], v[192:195], v[60:63]
	v_mfma_f32_16x16x32_bf16 v[56:59], v[158:161], v[192:195], v[56:59]
	v_mfma_f32_16x16x32_bf16 v[44:47], v[150:153], v[202:205], v[44:47]
	v_mfma_f32_16x16x32_bf16 v[40:43], v[158:161], v[202:205], v[40:43]
	v_mfma_f32_16x16x32_bf16 v[28:31], v[150:153], v[210:213], v[28:31]
	v_mfma_f32_16x16x32_bf16 v[24:27], v[158:161], v[210:213], v[24:27]
	v_mfma_f32_16x16x32_bf16 v[12:15], v[150:153], v[218:221], v[12:15]
	v_mfma_f32_16x16x32_bf16 v[8:11], v[158:161], v[218:221], v[8:11]
	v_mfma_f32_16x16x32_bf16 v[60:63], v[154:157], v[196:199], v[60:63]
	v_mfma_f32_16x16x32_bf16 v[56:59], v[168:171], v[196:199], v[56:59]
	v_mfma_f32_16x16x32_bf16 v[44:47], v[154:157], v[206:209], v[44:47]
	v_mfma_f32_16x16x32_bf16 v[40:43], v[168:171], v[206:209], v[40:43]
	v_mfma_f32_16x16x32_bf16 v[28:31], v[154:157], v[214:217], v[28:31]
	v_mfma_f32_16x16x32_bf16 v[24:27], v[168:171], v[214:217], v[24:27]
	v_mfma_f32_16x16x32_bf16 v[12:15], v[154:157], v[222:225], v[12:15]
	v_mfma_f32_16x16x32_bf16 v[8:11], v[168:171], v[222:225], v[8:11]
	s_setprio 1
	s_setprio 0
	v_mfma_f32_16x16x32_bf16 v[52:55], v[172:175], v[192:195], v[52:55]
	v_mfma_f32_16x16x32_bf16 v[48:51], v[184:187], v[192:195], v[48:51]
	v_mfma_f32_16x16x32_bf16 v[36:39], v[172:175], v[202:205], v[36:39]
	v_mfma_f32_16x16x32_bf16 v[32:35], v[184:187], v[202:205], v[32:35]
	v_mfma_f32_16x16x32_bf16 v[20:23], v[172:175], v[210:213], v[20:23]
	v_mfma_f32_16x16x32_bf16 v[16:19], v[184:187], v[210:213], v[16:19]
	v_mfma_f32_16x16x32_bf16 v[4:7], v[172:175], v[218:221], v[4:7]
	v_mfma_f32_16x16x32_bf16 v[0:3], v[184:187], v[218:221], v[0:3]
	v_mfma_f32_16x16x32_bf16 v[52:55], v[180:183], v[196:199], v[52:55]
	v_mfma_f32_16x16x32_bf16 v[48:51], v[188:191], v[196:199], v[48:51]
	v_mfma_f32_16x16x32_bf16 v[36:39], v[180:183], v[206:209], v[36:39]
	v_mfma_f32_16x16x32_bf16 v[32:35], v[188:191], v[206:209], v[32:35]
	v_mfma_f32_16x16x32_bf16 v[20:23], v[180:183], v[214:217], v[20:23]
	v_mfma_f32_16x16x32_bf16 v[16:19], v[188:191], v[214:217], v[16:19]
	v_mfma_f32_16x16x32_bf16 v[4:7], v[180:183], v[222:225], v[4:7]
	v_mfma_f32_16x16x32_bf16 v[0:3], v[188:191], v[222:225], v[0:3]
	s_setprio 1
	s_barrier
	s_add_i32 s63, 0, 0x18000
	s_add_i32 s64, 0, 0x1c000
	v_add_u32_e32 v168, s63, v143
	v_add_u32_e32 v178, s64, v143
	ds_read_b128 v[150:153], v168
	ds_read_b128 v[154:157], v168 offset:1024
	ds_read_b128 v[158:161], v168 offset:2048
	ds_read_b128 v[168:171], v168 offset:3072
	ds_read_b128 v[172:175], v178
	ds_read_b128 v[180:183], v178 offset:1024
	ds_read_b128 v[184:187], v178 offset:2048
	ds_read_b128 v[188:191], v178 offset:3072
	s_add_u32 s34, s34, 0x40000
	s_addc_u32 s35, s35, 0
	s_mov_b32 m0, s76
	v_lshl_add_u64 v[232:233], s[34:35], 0, v[128:129]
	ds_read_b128 v[192:195], v166 offset:32768
	ds_read_b128 v[196:199], v166 offset:33792
	ds_read_b128 v[202:205], v166 offset:34816
	ds_read_b128 v[206:209], v166 offset:35840
	ds_read_b128 v[210:213], v166 offset:36864
	ds_read_b128 v[214:217], v166 offset:37888
	ds_read_b128 v[218:221], v166 offset:38912
	ds_read_b128 v[222:225], v166 offset:39936
	global_load_lds_dwordx4 v[232:233], off
	v_lshl_add_u64 v[232:233], s[34:35], 0, v[132:133]
	s_mov_b32 m0, s77
	s_nop 0
	global_load_lds_dwordx4 v[232:233], off
	s_waitcnt vmcnt(8)
	s_waitcnt lgkmcnt(0)
	s_barrier
	s_setprio 0
	s_waitcnt lgkmcnt(0)
	v_mfma_f32_16x16x32_bf16 v[124:127], v[150:153], v[192:195], v[124:127]
	v_mfma_f32_16x16x32_bf16 v[120:123], v[158:161], v[192:195], v[120:123]
	v_mfma_f32_16x16x32_bf16 v[108:111], v[150:153], v[202:205], v[108:111]
	v_mfma_f32_16x16x32_bf16 v[104:107], v[158:161], v[202:205], v[104:107]
	v_mfma_f32_16x16x32_bf16 v[92:95], v[150:153], v[210:213], v[92:95]
	v_mfma_f32_16x16x32_bf16 v[88:91], v[158:161], v[210:213], v[88:91]
	v_mfma_f32_16x16x32_bf16 v[76:79], v[150:153], v[218:221], v[76:79]
	v_mfma_f32_16x16x32_bf16 v[72:75], v[158:161], v[218:221], v[72:75]
	v_mfma_f32_16x16x32_bf16 v[124:127], v[154:157], v[196:199], v[124:127]
	v_mfma_f32_16x16x32_bf16 v[120:123], v[168:171], v[196:199], v[120:123]
	v_mfma_f32_16x16x32_bf16 v[108:111], v[154:157], v[206:209], v[108:111]
	v_mfma_f32_16x16x32_bf16 v[104:107], v[168:171], v[206:209], v[104:107]
	v_mfma_f32_16x16x32_bf16 v[92:95], v[154:157], v[214:217], v[92:95]
	v_mfma_f32_16x16x32_bf16 v[88:91], v[168:171], v[214:217], v[88:91]
	v_mfma_f32_16x16x32_bf16 v[76:79], v[154:157], v[222:225], v[76:79]
	v_mfma_f32_16x16x32_bf16 v[72:75], v[168:171], v[222:225], v[72:75]
	s_setprio 1
	s_setprio 0
	v_mfma_f32_16x16x32_bf16 v[116:119], v[172:175], v[192:195], v[116:119]
	v_mfma_f32_16x16x32_bf16 v[112:115], v[184:187], v[192:195], v[112:115]
	v_mfma_f32_16x16x32_bf16 v[100:103], v[172:175], v[202:205], v[100:103]
	v_mfma_f32_16x16x32_bf16 v[96:99], v[184:187], v[202:205], v[96:99]
	v_mfma_f32_16x16x32_bf16 v[84:87], v[172:175], v[210:213], v[84:87]
	v_mfma_f32_16x16x32_bf16 v[80:83], v[184:187], v[210:213], v[80:83]
	v_mfma_f32_16x16x32_bf16 v[68:71], v[172:175], v[218:221], v[68:71]
	v_mfma_f32_16x16x32_bf16 v[64:67], v[184:187], v[218:221], v[64:67]
	v_mfma_f32_16x16x32_bf16 v[116:119], v[180:183], v[196:199], v[116:119]
	v_mfma_f32_16x16x32_bf16 v[112:115], v[188:191], v[196:199], v[112:115]
	v_mfma_f32_16x16x32_bf16 v[100:103], v[180:183], v[206:209], v[100:103]
	v_mfma_f32_16x16x32_bf16 v[96:99], v[188:191], v[206:209], v[96:99]
	v_mfma_f32_16x16x32_bf16 v[84:87], v[180:183], v[214:217], v[84:87]
	v_mfma_f32_16x16x32_bf16 v[80:83], v[188:191], v[214:217], v[80:83]
	v_mfma_f32_16x16x32_bf16 v[68:71], v[180:183], v[222:225], v[68:71]
	v_mfma_f32_16x16x32_bf16 v[64:67], v[188:191], v[222:225], v[64:67]
	s_setprio 1
	s_barrier
; #define PG8_STAGE(bufoff, gbase, voff) do { _Pragma("unroll") for (int _i = 0; _i < 2; ++_i) \
;         __builtin_amdgcn_global_load_lds((const unsigned*)((const char*)(gbase) + (voff)[_i]), (LAS unsigned*)(lds + (bufoff) + ldsw + _i * 8192), 16, 0, 0); } while (0)
; #define PG8_LDA(dst, b, h) do { _Pragma("unroll") for (int m = 0; m < 4; ++m) _Pragma("unroll") for (int k = 0; k < 2; ++k) dst[m][k] = *(const LAS bf16x8*)(lds + PG8_SA(b, h) + aoff + m * 2048 + k * 1024); } while (0)
; #define PG8_MMA(ai, bj, At, Bt) do { __builtin_amdgcn_s_setprio(1); _Pragma("unroll") for (int m = 0; m < 4; ++m) _Pragma("unroll") for (int n = 0; n < 2; ++n) _Pragma("unroll") for (int k = 0; k < 2; ++k) \
;         acc[ai][bj][m][n] = __builtin_amdgcn_mfma_f32_16x16x32_bf16(Bt[n][k], At[m][k], acc[ai][bj][m][n], 0, 0, 0); __builtin_amdgcn_s_setprio(0); } while (0)
; #define PG8_WAIT_V(n) asm volatile("s_waitcnt vmcnt(" #n ")" ::: "memory")
; #define PG8_WAIT_L(n) asm volatile("s_waitcnt lgkmcnt(" #n ")" ::: "memory")
; #define PG8_BAR __builtin_amdgcn_s_barrier()
; #define PG8_SCHED __builtin_amdgcn_sched_barrier(0)
; template <class Epi, class Sched, bool ALIGN_EPI = false, bool SP2 = true>
; DI void gemm_phase(LAS unsigned char* lds, const Gemm g, const Sched& S, const Epi& E, f32x4 (&acc)[2][2][4][2]) {
;     ...
;         for (int t = 0; t < nt; t += 2) {
;     ...
;             PG8_LDA(At, 1, 1); PG8_STAGE(PG8_SB(1, 0), b3, voffB); PG8_STAGE(PG8_SB(1, 1), b3 + hstep, voffB); PG8_STAGE(PG8_SA(1, 0), a3, voffA);
;             PG8_WAIT_V(8); PG8_WAIT_L(0); PG8_BAR; PG8_MMA(1, 0, At, B0); PG8_MMA(1, 1, At, B1); PG8_BAR; PG8_SCHED;
	s_add_i32 s34, s63, s39
	v_lshl_add_u64 v[176:177], v[176:177], 0, s[14:15]
	s_mov_b32 m0, s34
	ds_read_b128 v[192:195], v166 offset:49152
	ds_read_b128 v[196:199], v166 offset:50176
	ds_read_b128 v[202:205], v166 offset:51200
	ds_read_b128 v[206:209], v166 offset:52224
	ds_read_b128 v[210:213], v166 offset:53248
	ds_read_b128 v[214:217], v166 offset:54272
	ds_read_b128 v[218:221], v166 offset:55296
	ds_read_b128 v[222:225], v166 offset:56320
	global_load_lds_dwordx4 v[176:177], off
	s_add_i32 m0, s34, 0x2000
	s_add_u32 s30, s30, 0x10080
	v_lshl_add_u64 v[176:177], v[226:227], 0, s[14:15]
	s_addc_u32 s31, s31, 0
	s_add_i32 s34, s64, s39
	global_load_lds_dwordx4 v[176:177], off
	v_lshl_add_u64 v[176:177], s[30:31], 0, v[130:131]
	s_mov_b32 m0, s34
	s_nop 0
	global_load_lds_dwordx4 v[176:177], off
	v_lshl_add_u64 v[176:177], s[30:31], 0, v[134:135]
	s_add_i32 m0, s34, 0x2000
	s_nop 0
	global_load_lds_dwordx4 v[176:177], off
	v_lshl_add_u64 v[176:177], v[228:229], 0, s[14:15]
	s_mov_b32 m0, s80
	s_nop 0
	global_load_lds_dwordx4 v[176:177], off
	v_lshl_add_u64 v[176:177], v[230:231], 0, s[14:15]
	s_mov_b32 m0, s81
	s_nop 0
	global_load_lds_dwordx4 v[176:177], off
	s_waitcnt vmcnt(8)
	s_waitcnt lgkmcnt(0)
	s_barrier
	s_setprio 0
	s_waitcnt lgkmcnt(0)
	v_mfma_f32_16x16x32_bf16 v[60:63], v[150:153], v[192:195], v[60:63]
	v_mfma_f32_16x16x32_bf16 v[56:59], v[158:161], v[192:195], v[56:59]
	v_mfma_f32_16x16x32_bf16 v[44:47], v[150:153], v[202:205], v[44:47]
	v_mfma_f32_16x16x32_bf16 v[40:43], v[158:161], v[202:205], v[40:43]
	v_mfma_f32_16x16x32_bf16 v[28:31], v[150:153], v[210:213], v[28:31]
	v_mfma_f32_16x16x32_bf16 v[24:27], v[158:161], v[210:213], v[24:27]
	v_mfma_f32_16x16x32_bf16 v[12:15], v[150:153], v[218:221], v[12:15]
	v_mfma_f32_16x16x32_bf16 v[8:11], v[158:161], v[218:221], v[8:11]
	v_mfma_f32_16x16x32_bf16 v[60:63], v[154:157], v[196:199], v[60:63]
	v_mfma_f32_16x16x32_bf16 v[56:59], v[168:171], v[196:199], v[56:59]
	v_mfma_f32_16x16x32_bf16 v[44:47], v[154:157], v[206:209], v[44:47]
	v_mfma_f32_16x16x32_bf16 v[40:43], v[168:171], v[206:209], v[40:43]
	v_mfma_f32_16x16x32_bf16 v[28:31], v[154:157], v[214:217], v[28:31]
	v_mfma_f32_16x16x32_bf16 v[24:27], v[168:171], v[214:217], v[24:27]
	v_mfma_f32_16x16x32_bf16 v[12:15], v[154:157], v[222:225], v[12:15]
	v_mfma_f32_16x16x32_bf16 v[8:11], v[168:171], v[222:225], v[8:11]
	s_setprio 1
	s_setprio 0
	v_mfma_f32_16x16x32_bf16 v[52:55], v[172:175], v[192:195], v[52:55]
	v_mfma_f32_16x16x32_bf16 v[48:51], v[184:187], v[192:195], v[48:51]
	v_mfma_f32_16x16x32_bf16 v[36:39], v[172:175], v[202:205], v[36:39]
	v_mfma_f32_16x16x32_bf16 v[32:35], v[184:187], v[202:205], v[32:35]
	v_mfma_f32_16x16x32_bf16 v[20:23], v[172:175], v[210:213], v[20:23]
	v_mfma_f32_16x16x32_bf16 v[16:19], v[184:187], v[210:213], v[16:19]
	v_mfma_f32_16x16x32_bf16 v[4:7], v[172:175], v[218:221], v[4:7]
	v_mfma_f32_16x16x32_bf16 v[0:3], v[184:187], v[218:221], v[0:3]
	v_mfma_f32_16x16x32_bf16 v[52:55], v[180:183], v[196:199], v[52:55]
	v_mfma_f32_16x16x32_bf16 v[48:51], v[188:191], v[196:199], v[48:51]
	v_mfma_f32_16x16x32_bf16 v[36:39], v[180:183], v[206:209], v[36:39]
	v_mfma_f32_16x16x32_bf16 v[32:35], v[188:191], v[206:209], v[32:35]
	v_mfma_f32_16x16x32_bf16 v[20:23], v[180:183], v[214:217], v[20:23]
	v_mfma_f32_16x16x32_bf16 v[16:19], v[188:191], v[214:217], v[16:19]
	v_mfma_f32_16x16x32_bf16 v[4:7], v[180:183], v[222:225], v[4:7]
	v_mfma_f32_16x16x32_bf16 v[0:3], v[188:191], v[222:225], v[0:3]
	s_setprio 1
	s_barrier
	s_add_i32 s62, s62, 2
	s_add_u32 s0, s0, 0x100
	s_addc_u32 s1, s1, 0
	s_add_u32 s54, s54, 0x100
	s_addc_u32 s55, s55, 0
	s_cmp_gt_u32 s62, 13
	s_cbranch_scc0 .LBB0_159
	s_and_b64 vcc, exec, s[16:17]
	s_cbranch_vccz .LBB0_162
	s_barrier

; #define PG8_STAGE(bufoff, gbase, voff) do { _Pragma("unroll") for (int _i = 0; _i < 2; ++_i) \
;         __builtin_amdgcn_global_load_lds((const unsigned*)((const char*)(gbase) + (voff)[_i]), (LAS unsigned*)(lds + (bufoff) + ldsw + _i * 8192), 16, 0, 0); } while (0)
; #define PG8_LDA(dst, b, h) do { _Pragma("unroll") for (int m = 0; m < 4; ++m) _Pragma("unroll") for (int k = 0; k < 2; ++k) dst[m][k] = *(const LAS bf16x8*)(lds + PG8_SA(b, h) + aoff + m * 2048 + k * 1024); } while (0)
; #define PG8_LDB(dst, b, h) do { _Pragma("unroll") for (int n = 0; n < 2; ++n) _Pragma("unroll") for (int k = 0; k < 2; ++k) dst[n][k] = *(const LAS bf16x8*)(lds + PG8_SB(b, h) + boff + n * 2048 + k * 1024); } while (0)
; #define PG8_MMA(ai, bj, At, Bt) do { __builtin_amdgcn_s_setprio(1); _Pragma("unroll") for (int m = 0; m < 4; ++m) _Pragma("unroll") for (int n = 0; n < 2; ++n) _Pragma("unroll") for (int k = 0; k < 2; ++k) \
;         acc[ai][bj][m][n] = __builtin_amdgcn_mfma_f32_16x16x32_bf16(Bt[n][k], At[m][k], acc[ai][bj][m][n], 0, 0, 0); __builtin_amdgcn_s_setprio(0); } while (0)
; #define PG8_WAIT_V(n) asm volatile("s_waitcnt vmcnt(" #n ")" ::: "memory")
; #define PG8_WAIT_L(n) asm volatile("s_waitcnt lgkmcnt(" #n ")" ::: "memory")
; #define PG8_BAR __builtin_amdgcn_s_barrier()
; #define PG8_SCHED __builtin_amdgcn_sched_barrier(0)
; template <class Epi, class Sched, bool ALIGN_EPI = false, bool SP2 = true>
; DI void gemm_phase(LAS unsigned char* lds, const Gemm g, const Sched& S, const Epi& E, f32x4 (&acc)[2][2][4][2]) {
;     ...
;             PG8_LDB(B0, 0, 0); PG8_LDB(B1, 0, 1); PG8_SCHED; PG8_LDA(At, 0, 0); PG8_STAGE(PG8_SA(1, 1), a1 + hstep, voffA);
;             PG8_WAIT_V(8); PG8_WAIT_L(0); PG8_BAR; PG8_MMA(0, 0, At, B0); PG8_MMA(0, 1, At, B1); PG8_BAR; PG8_SCHED;
;             PG8_LDA(At, 0, 1); PG8_STAGE(PG8_SB(0, 0), b2, voffB); PG8_STAGE(PG8_SB(0, 1), b2 + hstep, voffB); PG8_STAGE(PG8_SA(0, 0), a2, voffA);
;             PG8_WAIT_V(8); PG8_WAIT_L(0); PG8_BAR; PG8_MMA(1, 0, At, B0); PG8_MMA(1, 1, At, B1); PG8_BAR; PG8_SCHED;
.LBB0_541:
	v_add_u32_e32 v156, s35, v142
	v_add_u32_e32 v172, s36, v142
	s_add_u32 s18, s0, s16
	ds_read_b128 v[144:147], v156
	ds_read_b128 v[148:151], v156 offset:1024
	ds_read_b128 v[152:155], v156 offset:2048
	ds_read_b128 v[156:159], v156 offset:3072
	ds_read_b128 v[160:163], v172
	ds_read_b128 v[164:167], v172 offset:1024
	ds_read_b128 v[168:171], v172 offset:2048
	ds_read_b128 v[172:175], v172 offset:3072
	s_addc_u32 s19, s1, s17
	s_add_u32 s18, s18, 0x100
	s_addc_u32 s19, s19, 0
	s_add_u32 s60, s52, s16
	s_addc_u32 s61, s53, s17
	s_cmpk_eq_i32 s16, 0x700
	s_cselect_b32 s21, s55, s19
	s_cselect_b32 s20, s56, s18
	s_cselect_b32 s19, s57, s61
	s_cselect_b32 s18, s58, s60
	s_mov_b32 m0, s37
	v_lshl_add_u64 v[176:177], v[136:137], 0, s[16:17]
	ds_read_b128 v[180:183], v143
	ds_read_b128 v[184:187], v143 offset:1024
	ds_read_b128 v[188:191], v143 offset:2048
	ds_read_b128 v[192:195], v143 offset:3072
	ds_read_b128 v[196:199], v143 offset:4096
	ds_read_b128 v[202:205], v143 offset:5120
	ds_read_b128 v[206:209], v143 offset:6144
	ds_read_b128 v[210:213], v143 offset:7168
	global_load_lds_dwordx4 v[176:177], off
	v_lshl_add_u64 v[176:177], v[138:139], 0, s[16:17]
	s_mov_b32 m0, s38
	s_nop 0
	global_load_lds_dwordx4 v[176:177], off
	s_waitcnt vmcnt(8)
	s_waitcnt lgkmcnt(0)
	s_barrier
	s_setprio 0
	s_waitcnt lgkmcnt(0)
	v_mfma_f32_16x16x32_bf16 v[124:127], v[144:147], v[180:183], v[124:127]
	v_mfma_f32_16x16x32_bf16 v[112:115], v[152:155], v[180:183], v[112:115]
	v_mfma_f32_16x16x32_bf16 v[104:107], v[144:147], v[188:191], v[104:107]
	v_mfma_f32_16x16x32_bf16 v[96:99], v[152:155], v[188:191], v[96:99]
	v_mfma_f32_16x16x32_bf16 v[100:103], v[144:147], v[196:199], v[100:103]
	v_mfma_f32_16x16x32_bf16 v[88:91], v[152:155], v[196:199], v[88:91]
	v_mfma_f32_16x16x32_bf16 v[92:95], v[144:147], v[206:209], v[92:95]
	v_mfma_f32_16x16x32_bf16 v[84:87], v[152:155], v[206:209], v[84:87]
	v_mfma_f32_16x16x32_bf16 v[124:127], v[148:151], v[184:187], v[124:127]
	v_mfma_f32_16x16x32_bf16 v[112:115], v[156:159], v[184:187], v[112:115]
	v_mfma_f32_16x16x32_bf16 v[104:107], v[148:151], v[192:195], v[104:107]
	v_mfma_f32_16x16x32_bf16 v[96:99], v[156:159], v[192:195], v[96:99]
	v_mfma_f32_16x16x32_bf16 v[100:103], v[148:151], v[202:205], v[100:103]
	v_mfma_f32_16x16x32_bf16 v[88:91], v[156:159], v[202:205], v[88:91]
	v_mfma_f32_16x16x32_bf16 v[92:95], v[148:151], v[210:213], v[92:95]
	v_mfma_f32_16x16x32_bf16 v[84:87], v[156:159], v[210:213], v[84:87]
	s_setprio 1
	s_setprio 0
	v_mfma_f32_16x16x32_bf16 v[80:83], v[160:163], v[180:183], v[80:83]
	v_mfma_f32_16x16x32_bf16 v[60:63], v[168:171], v[180:183], v[60:63]
	v_mfma_f32_16x16x32_bf16 v[56:59], v[160:163], v[188:191], v[56:59]
	v_mfma_f32_16x16x32_bf16 v[48:51], v[168:171], v[188:191], v[48:51]
	v_mfma_f32_16x16x32_bf16 v[52:55], v[160:163], v[196:199], v[52:55]
	v_mfma_f32_16x16x32_bf16 v[40:43], v[168:171], v[196:199], v[40:43]
	v_mfma_f32_16x16x32_bf16 v[44:47], v[160:163], v[206:209], v[44:47]
	v_mfma_f32_16x16x32_bf16 v[20:23], v[168:171], v[206:209], v[20:23]
	v_mfma_f32_16x16x32_bf16 v[80:83], v[164:167], v[184:187], v[80:83]
	v_mfma_f32_16x16x32_bf16 v[60:63], v[172:175], v[184:187], v[60:63]
	v_mfma_f32_16x16x32_bf16 v[56:59], v[164:167], v[192:195], v[56:59]
	v_mfma_f32_16x16x32_bf16 v[48:51], v[172:175], v[192:195], v[48:51]
	v_mfma_f32_16x16x32_bf16 v[52:55], v[164:167], v[202:205], v[52:55]
	v_mfma_f32_16x16x32_bf16 v[40:43], v[172:175], v[202:205], v[40:43]
	v_mfma_f32_16x16x32_bf16 v[44:47], v[164:167], v[210:213], v[44:47]
	v_mfma_f32_16x16x32_bf16 v[20:23], v[172:175], v[210:213], v[20:23]
	s_setprio 1
	s_barrier
	s_mov_b32 m0, s39
	v_lshl_add_u64 v[176:177], s[18:19], 0, v[130:131]
	s_add_u32 s60, s18, 0x40000
	ds_read_b128 v[180:183], v143 offset:16384
	ds_read_b128 v[184:187], v143 offset:17408
	ds_read_b128 v[188:191], v143 offset:18432
	ds_read_b128 v[192:195], v143 offset:19456
	ds_read_b128 v[196:199], v143 offset:20480
	ds_read_b128 v[202:205], v143 offset:21504
	ds_read_b128 v[206:209], v143 offset:22528
	ds_read_b128 v[210:213], v143 offset:23552
	global_load_lds_dwordx4 v[176:177], off
	v_lshl_add_u64 v[214:215], s[18:19], 0, v[128:129]
	s_mov_b32 m0, s40
	s_addc_u32 s61, s19, 0
	global_load_lds_dwordx4 v[214:215], off
	v_lshl_add_u64 v[216:217], s[60:61], 0, v[130:131]
	s_mov_b32 m0, s41
	v_lshl_add_u64 v[218:219], s[20:21], 0, v[128:129]
	global_load_lds_dwordx4 v[216:217], off
	v_lshl_add_u64 v[216:217], s[60:61], 0, v[128:129]
	s_mov_b32 m0, s42
	s_nop 0
	global_load_lds_dwordx4 v[216:217], off
	v_lshl_add_u64 v[216:217], s[20:21], 0, v[130:131]
	s_mov_b32 m0, s5
	s_nop 0
	global_load_lds_dwordx4 v[216:217], off
	s_mov_b32 m0, s27
	s_nop 0
	global_load_lds_dwordx4 v[218:219], off
	s_waitcnt vmcnt(8)
	s_waitcnt lgkmcnt(0)
	s_barrier
; #define PG8_STAGE(bufoff, gbase, voff) do { _Pragma("unroll") for (int _i = 0; _i < 2; ++_i) \
;         __builtin_amdgcn_global_load_lds((const unsigned*)((const char*)(gbase) + (voff)[_i]), (LAS unsigned*)(lds + (bufoff) + ldsw + _i * 8192), 16, 0, 0); } while (0)
; #define PG8_LDA(dst, b, h) do { _Pragma("unroll") for (int m = 0; m < 4; ++m) _Pragma("unroll") for (int k = 0; k < 2; ++k) dst[m][k] = *(const LAS bf16x8*)(lds + PG8_SA(b, h) + aoff + m * 2048 + k * 1024); } while (0)
; #define PG8_LDB(dst, b, h) do { _Pragma("unroll") for (int n = 0; n < 2; ++n) _Pragma("unroll") for (int k = 0; k < 2; ++k) dst[n][k] = *(const LAS bf16x8*)(lds + PG8_SB(b, h) + boff + n * 2048 + k * 1024); } while (0)
; #define PG8_MMA(ai, bj, At, Bt) do { __builtin_amdgcn_s_setprio(1); _Pragma("unroll") for (int m = 0; m < 4; ++m) _Pragma("unroll") for (int n = 0; n < 2; ++n) _Pragma("unroll") for (int k = 0; k < 2; ++k) \
;         acc[ai][bj][m][n] = __builtin_amdgcn_mfma_f32_16x16x32_bf16(Bt[n][k], At[m][k], acc[ai][bj][m][n], 0, 0, 0); __builtin_amdgcn_s_setprio(0); } while (0)
; #define PG8_WAIT_V(n) asm volatile("s_waitcnt vmcnt(" #n ")" ::: "memory")
; #define PG8_WAIT_L(n) asm volatile("s_waitcnt lgkmcnt(" #n ")" ::: "memory")
; #define PG8_BAR __builtin_amdgcn_s_barrier()
; #define PG8_SCHED __builtin_amdgcn_sched_barrier(0)
; template <class Epi, class Sched, bool ALIGN_EPI = false, bool SP2 = true>
; DI void gemm_phase(LAS unsigned char* lds, const Gemm g, const Sched& S, const Epi& E, f32x4 (&acc)[2][2][4][2]) {
;     ...
;             PG8_WAIT_V(8); PG8_WAIT_L(0); PG8_BAR; PG8_MMA(1, 0, At, B0); PG8_MMA(1, 1, At, B1); PG8_BAR; PG8_SCHED;
;             PG8_LDB(B0, 1, 0); PG8_LDB(B1, 1, 1); PG8_SCHED; PG8_LDA(At, 1, 0); PG8_STAGE(PG8_SA(0, 1), a2 + hstep, voffA);
;             PG8_WAIT_V(8); PG8_WAIT_L(0); PG8_BAR; PG8_MMA(0, 0, At, B0); PG8_MMA(0, 1, At, B1); PG8_BAR; PG8_SCHED;
	s_setprio 0
	s_waitcnt lgkmcnt(0)
	v_mfma_f32_16x16x32_bf16 v[76:79], v[144:147], v[180:183], v[76:79]
	v_mfma_f32_16x16x32_bf16 v[36:39], v[152:155], v[180:183], v[36:39]
	v_mfma_f32_16x16x32_bf16 v[68:71], v[144:147], v[188:191], v[68:71]
	v_mfma_f32_16x16x32_bf16 v[28:31], v[152:155], v[188:191], v[28:31]
	v_mfma_f32_16x16x32_bf16 v[72:75], v[144:147], v[196:199], v[72:75]
	v_mfma_f32_16x16x32_bf16 v[32:35], v[152:155], v[196:199], v[32:35]
	v_mfma_f32_16x16x32_bf16 v[64:67], v[144:147], v[206:209], v[64:67]
	v_mfma_f32_16x16x32_bf16 v[24:27], v[152:155], v[206:209], v[24:27]
	v_mfma_f32_16x16x32_bf16 v[76:79], v[148:151], v[184:187], v[76:79]
	v_mfma_f32_16x16x32_bf16 v[36:39], v[156:159], v[184:187], v[36:39]
	v_mfma_f32_16x16x32_bf16 v[68:71], v[148:151], v[192:195], v[68:71]
	v_mfma_f32_16x16x32_bf16 v[28:31], v[156:159], v[192:195], v[28:31]
	v_mfma_f32_16x16x32_bf16 v[72:75], v[148:151], v[202:205], v[72:75]
	v_mfma_f32_16x16x32_bf16 v[32:35], v[156:159], v[202:205], v[32:35]
	v_mfma_f32_16x16x32_bf16 v[64:67], v[148:151], v[210:213], v[64:67]
	v_mfma_f32_16x16x32_bf16 v[24:27], v[156:159], v[210:213], v[24:27]
	s_setprio 1
	s_setprio 0
	v_mfma_f32_16x16x32_bf16 v[16:19], v[160:163], v[180:183], v[16:19]
	v_mfma_f32_16x16x32_bf16 v[8:11], v[168:171], v[180:183], v[8:11]
	v_mfma_f32_16x16x32_bf16 v[12:15], v[160:163], v[188:191], v[12:15]
	v_mfma_f32_16x16x32_bf16 v[0:3], v[168:171], v[188:191], v[0:3]
	v_mfma_f32_16x16x32_bf16 v[4:7], v[160:163], v[196:199], v[4:7]
	v_mfma_f32_16x16x32_bf16 v[108:111], v[168:171], v[196:199], v[108:111]
	v_mfma_f32_16x16x32_bf16 v[120:123], v[160:163], v[206:209], v[120:123]
	v_mfma_f32_16x16x32_bf16 v[116:119], v[168:171], v[206:209], v[116:119]
	v_mfma_f32_16x16x32_bf16 v[16:19], v[164:167], v[184:187], v[16:19]
	v_mfma_f32_16x16x32_bf16 v[8:11], v[172:175], v[184:187], v[8:11]
	v_mfma_f32_16x16x32_bf16 v[12:15], v[164:167], v[192:195], v[12:15]
	v_mfma_f32_16x16x32_bf16 v[0:3], v[172:175], v[192:195], v[0:3]
	v_mfma_f32_16x16x32_bf16 v[4:7], v[164:167], v[202:205], v[4:7]
	v_mfma_f32_16x16x32_bf16 v[108:111], v[172:175], v[202:205], v[108:111]
	v_mfma_f32_16x16x32_bf16 v[120:123], v[164:167], v[210:213], v[120:123]
	v_mfma_f32_16x16x32_bf16 v[116:119], v[172:175], v[210:213], v[116:119]
	s_setprio 1
	s_barrier
	v_add_u32_e32 v156, s43, v142
	v_add_u32_e32 v172, s44, v142
	ds_read_b128 v[144:147], v156
	ds_read_b128 v[148:151], v156 offset:1024
	ds_read_b128 v[152:155], v156 offset:2048
	ds_read_b128 v[156:159], v156 offset:3072
	ds_read_b128 v[160:163], v172
	ds_read_b128 v[164:167], v172 offset:1024
	ds_read_b128 v[168:171], v172 offset:2048
	ds_read_b128 v[172:175], v172 offset:3072
	s_add_u32 s20, s20, 0x40000
	s_addc_u32 s21, s21, 0
	s_mov_b32 m0, s28
	v_lshl_add_u64 v[220:221], s[20:21], 0, v[130:131]
	ds_read_b128 v[180:183], v143 offset:32768
	ds_read_b128 v[184:187], v143 offset:33792
	ds_read_b128 v[188:191], v143 offset:34816
	ds_read_b128 v[192:195], v143 offset:35840
	ds_read_b128 v[196:199], v143 offset:36864
	ds_read_b128 v[202:205], v143 offset:37888
	ds_read_b128 v[206:209], v143 offset:38912
	ds_read_b128 v[210:213], v143 offset:39936
	global_load_lds_dwordx4 v[220:221], off
	v_lshl_add_u64 v[220:221], s[20:21], 0, v[128:129]
	s_mov_b32 m0, s29
	s_nop 0
	global_load_lds_dwordx4 v[220:221], off
	s_waitcnt vmcnt(8)
	s_waitcnt lgkmcnt(0)
	s_barrier
	s_setprio 0
	s_waitcnt lgkmcnt(0)
	v_mfma_f32_16x16x32_bf16 v[124:127], v[144:147], v[180:183], v[124:127]
	v_mfma_f32_16x16x32_bf16 v[112:115], v[152:155], v[180:183], v[112:115]
	v_mfma_f32_16x16x32_bf16 v[104:107], v[144:147], v[188:191], v[104:107]
	v_mfma_f32_16x16x32_bf16 v[96:99], v[152:155], v[188:191], v[96:99]
	v_mfma_f32_16x16x32_bf16 v[100:103], v[144:147], v[196:199], v[100:103]
	v_mfma_f32_16x16x32_bf16 v[88:91], v[152:155], v[196:199], v[88:91]
	v_mfma_f32_16x16x32_bf16 v[92:95], v[144:147], v[206:209], v[92:95]
	v_mfma_f32_16x16x32_bf16 v[84:87], v[152:155], v[206:209], v[84:87]
	v_mfma_f32_16x16x32_bf16 v[124:127], v[148:151], v[184:187], v[124:127]
	v_mfma_f32_16x16x32_bf16 v[112:115], v[156:159], v[184:187], v[112:115]
	v_mfma_f32_16x16x32_bf16 v[104:107], v[148:151], v[192:195], v[104:107]
	v_mfma_f32_16x16x32_bf16 v[96:99], v[156:159], v[192:195], v[96:99]
	v_mfma_f32_16x16x32_bf16 v[100:103], v[148:151], v[202:205], v[100:103]
	v_mfma_f32_16x16x32_bf16 v[88:91], v[156:159], v[202:205], v[88:91]
	v_mfma_f32_16x16x32_bf16 v[92:95], v[148:151], v[210:213], v[92:95]
	v_mfma_f32_16x16x32_bf16 v[84:87], v[156:159], v[210:213], v[84:87]
	s_setprio 1
	s_setprio 0
	v_mfma_f32_16x16x32_bf16 v[80:83], v[160:163], v[180:183], v[80:83]
	v_mfma_f32_16x16x32_bf16 v[60:63], v[168:171], v[180:183], v[60:63]
	v_mfma_f32_16x16x32_bf16 v[56:59], v[160:163], v[188:191], v[56:59]
	v_mfma_f32_16x16x32_bf16 v[48:51], v[168:171], v[188:191], v[48:51]
	v_mfma_f32_16x16x32_bf16 v[52:55], v[160:163], v[196:199], v[52:55]
	v_mfma_f32_16x16x32_bf16 v[40:43], v[168:171], v[196:199], v[40:43]
	v_mfma_f32_16x16x32_bf16 v[44:47], v[160:163], v[206:209], v[44:47]
	v_mfma_f32_16x16x32_bf16 v[20:23], v[168:171], v[206:209], v[20:23]
	v_mfma_f32_16x16x32_bf16 v[80:83], v[164:167], v[184:187], v[80:83]
	v_mfma_f32_16x16x32_bf16 v[60:63], v[172:175], v[184:187], v[60:63]
	v_mfma_f32_16x16x32_bf16 v[56:59], v[164:167], v[192:195], v[56:59]
	v_mfma_f32_16x16x32_bf16 v[48:51], v[172:175], v[192:195], v[48:51]
	v_mfma_f32_16x16x32_bf16 v[52:55], v[164:167], v[202:205], v[52:55]
	v_mfma_f32_16x16x32_bf16 v[40:43], v[172:175], v[202:205], v[40:43]
	v_mfma_f32_16x16x32_bf16 v[44:47], v[164:167], v[210:213], v[44:47]
	v_mfma_f32_16x16x32_bf16 v[20:23], v[172:175], v[210:213], v[20:23]
	s_setprio 1
	s_barrier
; #define PG8_STAGE(bufoff, gbase, voff) do { _Pragma("unroll") for (int _i = 0; _i < 2; ++_i) \
;         __builtin_amdgcn_global_load_lds((const unsigned*)((const char*)(gbase) + (voff)[_i]), (LAS unsigned*)(lds + (bufoff) + ldsw + _i * 8192), 16, 0, 0); } while (0)
; #define PG8_LDA(dst, b, h) do { _Pragma("unroll") for (int m = 0; m < 4; ++m) _Pragma("unroll") for (int k = 0; k < 2; ++k) dst[m][k] = *(const LAS bf16x8*)(lds + PG8_SA(b, h) + aoff + m * 2048 + k * 1024); } while (0)
; #define PG8_MMA(ai, bj, At, Bt) do { __builtin_amdgcn_s_setprio(1); _Pragma("unroll") for (int m = 0; m < 4; ++m) _Pragma("unroll") for (int n = 0; n < 2; ++n) _Pragma("unroll") for (int k = 0; k < 2; ++k) \
;         acc[ai][bj][m][n] = __builtin_amdgcn_mfma_f32_16x16x32_bf16(Bt[n][k], At[m][k], acc[ai][bj][m][n], 0, 0, 0); __builtin_amdgcn_s_setprio(0); } while (0)
; #define PG8_WAIT_V(n) asm volatile("s_waitcnt vmcnt(" #n ")" ::: "memory")
; #define PG8_WAIT_L(n) asm volatile("s_waitcnt lgkmcnt(" #n ")" ::: "memory")
; #define PG8_BAR __builtin_amdgcn_s_barrier()
; #define PG8_SCHED __builtin_amdgcn_sched_barrier(0)
; template <class Epi, class Sched, bool ALIGN_EPI = false, bool SP2 = true>
; DI void gemm_phase(LAS unsigned char* lds, const Gemm g, const Sched& S, const Epi& E, f32x4 (&acc)[2][2][4][2]) {
;     ...
;     for (;;) {
;         const bool has_next = S.next(ui + 1, nxt);
;         const char* nA = has_next ? (const char*)g.A + (size_t)nxt.pm * tstep : cA; const char* nB = has_next ? (const char*)g.Bt + (size_t)nxt.pn * tstep : cB;
;         for (int t = 0; t < nt; t += 2) {
;     ...
;             PG8_LDA(At, 1, 1); PG8_STAGE(PG8_SB(1, 0), b3, voffB); PG8_STAGE(PG8_SB(1, 1), b3 + hstep, voffB); PG8_STAGE(PG8_SA(1, 0), a3, voffA);
;             PG8_WAIT_V(8); PG8_WAIT_L(0); PG8_BAR; PG8_MMA(1, 0, At, B0); PG8_MMA(1, 1, At, B1); PG8_BAR; PG8_SCHED;
	s_mov_b32 m0, s45
	v_lshl_add_u64 v[176:177], v[176:177], 0, s[6:7]
	s_add_u32 s18, s18, 0x40080
	ds_read_b128 v[180:183], v143 offset:49152
	ds_read_b128 v[184:187], v143 offset:50176
	ds_read_b128 v[188:191], v143 offset:51200
	ds_read_b128 v[192:195], v143 offset:52224
	ds_read_b128 v[196:199], v143 offset:53248
	ds_read_b128 v[202:205], v143 offset:54272
	ds_read_b128 v[206:209], v143 offset:55296
	ds_read_b128 v[210:213], v143 offset:56320
	global_load_lds_dwordx4 v[176:177], off
	v_lshl_add_u64 v[176:177], v[214:215], 0, s[6:7]
	s_mov_b32 m0, s46
	s_addc_u32 s19, s19, 0
	global_load_lds_dwordx4 v[176:177], off
	v_lshl_add_u64 v[176:177], s[18:19], 0, v[130:131]
	s_mov_b32 m0, s47
	s_nop 0
	global_load_lds_dwordx4 v[176:177], off
	v_lshl_add_u64 v[176:177], s[18:19], 0, v[128:129]
	s_mov_b32 m0, s48
	s_nop 0
	global_load_lds_dwordx4 v[176:177], off
	v_lshl_add_u64 v[176:177], v[216:217], 0, s[6:7]
	s_mov_b32 m0, s31
	s_nop 0
	global_load_lds_dwordx4 v[176:177], off
	v_lshl_add_u64 v[176:177], v[218:219], 0, s[6:7]
	s_mov_b32 m0, s34
	s_nop 0
	global_load_lds_dwordx4 v[176:177], off
	s_waitcnt vmcnt(8)
	s_waitcnt lgkmcnt(0)
	s_barrier
	s_setprio 0
	s_waitcnt lgkmcnt(0)
	v_mfma_f32_16x16x32_bf16 v[76:79], v[144:147], v[180:183], v[76:79]
	v_mfma_f32_16x16x32_bf16 v[36:39], v[152:155], v[180:183], v[36:39]
	v_mfma_f32_16x16x32_bf16 v[68:71], v[144:147], v[188:191], v[68:71]
	v_mfma_f32_16x16x32_bf16 v[28:31], v[152:155], v[188:191], v[28:31]
	v_mfma_f32_16x16x32_bf16 v[72:75], v[144:147], v[196:199], v[72:75]
	v_mfma_f32_16x16x32_bf16 v[32:35], v[152:155], v[196:199], v[32:35]
	v_mfma_f32_16x16x32_bf16 v[64:67], v[144:147], v[206:209], v[64:67]
	v_mfma_f32_16x16x32_bf16 v[24:27], v[152:155], v[206:209], v[24:27]
	v_mfma_f32_16x16x32_bf16 v[76:79], v[148:151], v[184:187], v[76:79]
	v_mfma_f32_16x16x32_bf16 v[36:39], v[156:159], v[184:187], v[36:39]
	v_mfma_f32_16x16x32_bf16 v[68:71], v[148:151], v[192:195], v[68:71]
	v_mfma_f32_16x16x32_bf16 v[28:31], v[156:159], v[192:195], v[28:31]
	v_mfma_f32_16x16x32_bf16 v[72:75], v[148:151], v[202:205], v[72:75]
	v_mfma_f32_16x16x32_bf16 v[32:35], v[156:159], v[202:205], v[32:35]
	v_mfma_f32_16x16x32_bf16 v[64:67], v[148:151], v[210:213], v[64:67]
	v_mfma_f32_16x16x32_bf16 v[24:27], v[156:159], v[210:213], v[24:27]
	s_setprio 1
	s_setprio 0
	v_mfma_f32_16x16x32_bf16 v[16:19], v[160:163], v[180:183], v[16:19]
	v_mfma_f32_16x16x32_bf16 v[8:11], v[168:171], v[180:183], v[8:11]
	v_mfma_f32_16x16x32_bf16 v[12:15], v[160:163], v[188:191], v[12:15]
	v_mfma_f32_16x16x32_bf16 v[0:3], v[168:171], v[188:191], v[0:3]
	v_mfma_f32_16x16x32_bf16 v[4:7], v[160:163], v[196:199], v[4:7]
	v_mfma_f32_16x16x32_bf16 v[108:111], v[168:171], v[196:199], v[108:111]
	v_mfma_f32_16x16x32_bf16 v[120:123], v[160:163], v[206:209], v[120:123]
	v_mfma_f32_16x16x32_bf16 v[116:119], v[168:171], v[206:209], v[116:119]
	v_mfma_f32_16x16x32_bf16 v[16:19], v[164:167], v[184:187], v[16:19]
	v_mfma_f32_16x16x32_bf16 v[8:11], v[172:175], v[184:187], v[8:11]
	v_mfma_f32_16x16x32_bf16 v[12:15], v[164:167], v[192:195], v[12:15]
	v_mfma_f32_16x16x32_bf16 v[0:3], v[172:175], v[192:195], v[0:3]
	v_mfma_f32_16x16x32_bf16 v[4:7], v[164:167], v[202:205], v[4:7]
	v_mfma_f32_16x16x32_bf16 v[108:111], v[172:175], v[202:205], v[108:111]
	v_mfma_f32_16x16x32_bf16 v[120:123], v[164:167], v[210:213], v[120:123]
	v_mfma_f32_16x16x32_bf16 v[116:119], v[172:175], v[210:213], v[116:119]
	s_setprio 1
	s_barrier
	s_add_i32 s59, s59, 2
	s_add_u32 s16, s16, 0x100
	s_addc_u32 s17, s17, 0
	s_cmp_gt_u32 s59, 13
	s_cbranch_scc0 .LBB0_541
	s_add_u32 s16, s52, 0xffffff00
	s_addc_u32 s17, s53, -1
	s_andn2_b64 vcc, exec, s[12:13]
	s_cbranch_vccz .LBB0_539
	s_mov_b64 s[8:9], s[16:17]
	s_andn2_b64 vcc, exec, s[10:11]
	s_cbranch_vccnz .LBB0_540
